# conv epilogue gate loads issued at item setup into v222-v229 (loop-invariant constants re-materialised after use)
# speedup vs baseline: 1.1319x; 1.0005x over previous
.LBB0_691:
	v_readlane_b32 s16, v252, 0
	s_and_b64 s[0:1], s[36:37], exec
	v_readlane_b32 s24, v252, 8
	v_readlane_b32 s25, v252, 9
	v_readlane_b32 s26, v252, 10
	v_readlane_b32 s27, v252, 11
	s_cselect_b32 s3, s25, s27
	s_cselect_b32 s72, s24, s26
	s_lshr_b32 s73, s4, 5
	s_and_b64 s[0:1], s[36:37], exec
	s_cselect_b32 s74, 9, 12
	s_add_i32 s8, s2, 0xc00
	s_lshr_b32 s75, s4, 2
	s_mul_hi_i32 s9, s8, 0x6000
	s_mulk_i32 s8, 0x6000
	s_add_u32 s8, s90, s8
	s_addc_u32 s9, s91, s9
	s_lshl_b32 s5, s5, 1
	s_add_u32 s8, s8, s5
	s_addc_u32 s9, s9, 0
	v_readlane_b32 s10, v254, 31
	v_readlane_b32 s11, v254, 32
	s_add_u32 s6, s10, s6
	s_addc_u32 s11, s11, s14
	s_add_u32 s10, s6, s5
	s_addc_u32 s11, s11, 0
	s_and_b64 s[14:15], s[36:37], exec
	s_cselect_b32 s5, 8, 11
	v_cndmask_b32_e64 v0, v78, v76, s[36:37]
	v_cndmask_b32_e64 v3, v79, v77, s[36:37]
	v_lshlrev_b32_e32 v4, s5, v0
	v_lshl_add_u32 v5, v3, 5, v4
	v_or_b32_e32 v60, v5, v82
	v_ashrrev_i32_e32 v61, 31, v60
	v_lshlrev_b64 v[0:1], 1, v[60:61]
	v_lshl_add_u64 v[62:63], s[8:9], 0, v[0:1]
	global_load_dwordx2 v[222:223], v[62:63], off
	global_load_dwordx2 v[224:225], v[62:63], off offset:16
	global_load_dwordx2 v[226:227], v[62:63], off offset:32
	global_load_dwordx2 v[228:229], v[62:63], off offset:48
	v_lshl_add_u64 v[66:67], s[10:11], 0, v[0:1]
	v_ashrrev_i32_e32 v1, 1, v4
	v_lshl_add_u32 v1, v4, 1, v1
	v_cmp_gt_u32_e64 s[40:41], s73, v89
	v_lshl_or_b32 v121, v74, 1, v1
	v_cmp_gt_u32_e64 s[42:43], s73, v91
	v_cndmask_b32_e64 v1, 0, v90, s[40:41]
	v_lshl_add_u32 v122, v1, 1, v85
	v_cndmask_b32_e64 v1, 0, v92, s[42:43]
	v_cmp_gt_u32_e64 s[44:45], s73, v93
	v_lshl_add_u32 v124, v1, 1, v85
	v_cmp_gt_u32_e64 s[46:47], s73, v95
	v_cndmask_b32_e64 v1, 0, v94, s[44:45]
	v_lshl_add_u32 v125, v1, 1, v85
	v_cndmask_b32_e64 v1, 0, v96, s[46:47]
	v_cmp_gt_u32_e64 s[48:49], s73, v97
	v_lshl_add_u32 v126, v1, 1, v85
	v_cmp_gt_u32_e64 s[50:51], s73, v99
	v_cndmask_b32_e64 v1, 0, v98, s[48:49]
	v_lshl_add_u32 v127, v1, 1, v85
	v_cndmask_b32_e64 v1, 0, v100, s[50:51]
	v_cmp_gt_u32_e64 s[52:53], s73, v101
	v_lshl_add_u32 v128, v1, 1, v85
	v_cmp_gt_u32_e64 s[54:55], s73, v77
	v_cndmask_b32_e64 v1, 0, v102, s[52:53]
	v_lshl_add_u32 v129, v1, 1, v85
	v_cndmask_b32_e64 v1, 0, v103, s[54:55]
	v_cmp_gt_u32_e64 s[56:57], s73, v104
	v_lshl_add_u32 v130, v1, 1, v85
	v_cmp_gt_u32_e64 s[58:59], s73, v106
	v_cndmask_b32_e64 v1, 0, v105, s[56:57]
	v_lshl_add_u32 v131, v1, 1, v85
	v_cndmask_b32_e64 v1, 0, v107, s[58:59]
	v_cmp_gt_u32_e64 s[60:61], s73, v108
	v_lshl_add_u32 v136, v1, 1, v85
	v_cmp_gt_u32_e64 s[62:63], s73, v110
	v_cndmask_b32_e64 v1, 0, v109, s[60:61]
	v_lshl_add_u32 v141, v1, 1, v85
	v_cndmask_b32_e64 v1, 0, v111, s[62:63]
	v_cmp_gt_u32_e64 s[64:65], s73, v112
	v_lshl_add_u32 v146, v1, 1, v85
	v_cmp_gt_u32_e64 s[66:67], s73, v114
	v_cndmask_b32_e64 v1, 0, v113, s[64:65]
	v_ashrrev_i32_e32 v0, 1, v5
	v_lshl_add_u32 v151, v1, 1, v85
	v_cndmask_b32_e64 v1, 0, v115, s[66:67]
	v_cmp_gt_u32_e64 s[68:69], s73, v116
	v_lshl_add_u32 v55, v60, 1, v0
	v_cndmask_b32_e64 v0, v80, -7, s[36:37]
	v_lshl_add_u32 v156, v1, 1, v85
	v_cndmask_b32_e64 v1, 0, v117, s[68:69]
	v_add_u32_e32 v2, s4, v83
	v_lshl_add_u32 v161, v1, 1, v85
	s_lshl_b32 s4, s4, 1
	v_lshlrev_b32_e32 v1, 6, v0
	v_sub_u32_e32 v1, s4, v1
	v_lshl_add_u32 v123, v2, 1, v75
	v_add_u32_e32 v167, v120, v1
	v_mul_u32_u24_e32 v1, 40, v3
	v_mul_i32_i24_e32 v2, 40, v0
	s_mov_b32 s7, 0
	v_cmp_gt_i32_e64 s[0:1], s75, v64
	v_lshl_add_u64 v[68:69], s[8:9], 0, v[58:59]
	v_lshl_add_u64 v[70:71], s[10:11], 0, v[58:59]
	v_cndmask_b32_e64 v61, v81, 7, s[36:37]
	v_subrev_u32_e32 v132, 64, v123
	v_subrev_u32_e32 v133, 56, v123
	v_subrev_u32_e32 v134, 32, v123
	v_subrev_u32_e32 v135, 24, v123
	v_add_u32_e32 v137, 0xffffff80, v123
	v_add_u32_e32 v138, 0xffffff88, v123
	v_add_u32_e32 v139, 0xffffffa0, v123
	v_add_u32_e32 v140, 0xffffffa8, v123
	v_add_u32_e32 v142, 0xffffff40, v123
	v_add_u32_e32 v143, 0xffffff48, v123
	v_add_u32_e32 v144, 0xffffff60, v123
	v_add_u32_e32 v145, 0xffffff68, v123
	v_add_u32_e32 v147, 0xffffff00, v123
	v_add_u32_e32 v148, 0xffffff08, v123
	v_add_u32_e32 v149, 0xffffff20, v123
	v_add_u32_e32 v150, 0xffffff28, v123
	v_add_u32_e32 v152, 0xfffffec0, v123
	v_add_u32_e32 v153, 0xfffffec8, v123
	v_add_u32_e32 v154, 0xfffffee0, v123
	v_add_u32_e32 v155, 0xfffffee8, v123
	v_add_u32_e32 v157, 0xfffffe80, v123
	v_add_u32_e32 v158, 0xfffffe88, v123
	v_add_u32_e32 v159, 0xfffffea0, v123
	v_add_u32_e32 v160, 0xfffffea8, v123
	v_add_u32_e32 v162, 0xfffffe40, v123
	v_add_u32_e32 v163, 0xfffffe48, v123
	v_add_u32_e32 v164, 0xfffffe60, v123
	v_add_u32_e32 v165, 0xfffffe68, v123
	v_add_u32_e32 v166, -1, v0
	v_sub_u32_e32 v168, v1, v2
	v_sub_u32_e32 v169, v3, v0
	s_mov_b64 s[8:9], -1
	v_readlane_b32 s17, v252, 1
	v_readlane_b32 s18, v252, 2
	v_readlane_b32 s19, v252, 3
	v_readlane_b32 s20, v252, 4
	v_readlane_b32 s21, v252, 5
	v_readlane_b32 s22, v252, 6
	v_readlane_b32 s23, v252, 7
	v_readlane_b32 s28, v252, 12
	v_readlane_b32 s29, v252, 13
	v_readlane_b32 s30, v252, 14
	v_readlane_b32 s31, v252, 15
	s_branch .LBB0_693

.LBB0_711:
	s_waitcnt vmcnt(0)
	v_mov_b32_e32 v40, v222
	v_mov_b32_e32 v41, v223
	v_mov_b32_e32 v36, v224
	v_mov_b32_e32 v37, v225
	v_mov_b32_e32 v34, v226
	v_mov_b32_e32 v35, v227
	v_mov_b32_e32 v32, v228
	v_mov_b32_e32 v33, v229
	v_mov_b32_e32 v222, 0x980
	v_mov_b32_e32 v223, 0x680
	v_mov_b32_e32 v224, 0x900
	v_mov_b32_e32 v225, 0x700
	v_mov_b32_e32 v226, 0x880
	v_mov_b32_e32 v227, 0x780
	v_mov_b32_e32 v228, 0x800
	v_mov_b32_e32 v229, 0x1800
	s_mov_b32 s6, 0xbfb8aa3b
	s_mov_b32 s7, 0x42ce8ed0
	s_mov_b32 s8, 0xc2b17218
	s_waitcnt vmcnt(3)
	v_lshlrev_b32_e32 v38, 16, v40
	v_and_b32_e32 v44, 0xffff0000, v40
	v_lshlrev_b32_e32 v39, 16, v41
	v_and_b32_e32 v40, 0xffff0000, v41
	v_mul_f32_e32 v41, 0xbfb8aa3b, v38
	v_fma_f32 v42, v38, s6, -v41
	v_rndne_f32_e32 v43, v41
	v_fmac_f32_e32 v42, 0xb2a5705f, v38
	v_sub_f32_e32 v41, v41, v43
	v_add_f32_e32 v41, v41, v42
	v_exp_f32_e32 v41, v41
	v_cvt_i32_f32_e32 v42, v43
	v_cmp_nlt_f32_e32 vcc, s7, v38
	v_ldexp_f32 v41, v41, v42
	s_nop 0
	v_cndmask_b32_e32 v41, 0, v41, vcc
	v_cmp_ngt_f32_e32 vcc, s8, v38
	s_nop 1
	v_cndmask_b32_e32 v42, v192, v41, vcc
	v_mul_f32_e32 v41, 0xbfb8aa3b, v44
	v_fma_f32 v43, v44, s6, -v41
	v_rndne_f32_e32 v45, v41
	v_fmac_f32_e32 v43, 0xb2a5705f, v44
	v_sub_f32_e32 v41, v41, v45
	v_add_f32_e32 v41, v41, v43
	v_exp_f32_e32 v41, v41
	v_cvt_i32_f32_e32 v43, v45
	v_cmp_nlt_f32_e32 vcc, s7, v44
	v_ldexp_f32 v41, v41, v43
	s_nop 0
	v_cndmask_b32_e32 v41, 0, v41, vcc
	v_cmp_ngt_f32_e32 vcc, s8, v44
	s_nop 1
	v_cndmask_b32_e32 v43, v192, v41, vcc
	v_pk_add_f32 v[42:43], v[42:43], 1.0 op_sel_hi:[1,0]
	s_nop 0
	v_div_scale_f32 v41, s[4:5], v43, v43, v44
	v_rcp_f32_e32 v45, v41
	s_nop 0
	v_fma_f32 v46, -v41, v45, 1.0
	v_fmac_f32_e32 v45, v46, v45
	v_div_scale_f32 v46, vcc, v44, v43, v44
	v_mul_f32_e32 v47, v46, v45
	v_fma_f32 v48, -v41, v47, v46
	v_fmac_f32_e32 v47, v48, v45
	v_fma_f32 v41, -v41, v47, v46
	v_div_fmas_f32 v41, v41, v45, v47
	v_div_fixup_f32 v43, v41, v43, v44
	v_div_scale_f32 v41, s[4:5], v42, v42, v38
	v_rcp_f32_e32 v44, v41
	s_nop 0
	v_fma_f32 v45, -v41, v44, 1.0
	v_fmac_f32_e32 v44, v45, v44
	v_div_scale_f32 v45, vcc, v38, v42, v38
	v_mul_f32_e32 v46, v45, v44
	v_fma_f32 v47, -v41, v46, v45
	v_fmac_f32_e32 v46, v47, v44
	v_fma_f32 v41, -v41, v46, v45
	v_div_fmas_f32 v41, v41, v44, v46
	v_div_fixup_f32 v42, v41, v42, v38
	v_pk_mul_f32 v[42:43], v[0:1], v[42:43]
	v_mul_f32_e32 v41, 0xbfb8aa3b, v39
	v_cvt_pk_bf16_f32 v38, v42, v43
	v_fma_f32 v42, v39, s6, -v41
	v_rndne_f32_e32 v43, v41
	v_fmac_f32_e32 v42, 0xb2a5705f, v39
	v_sub_f32_e32 v41, v41, v43
	v_add_f32_e32 v41, v41, v42
	v_exp_f32_e32 v41, v41
	v_cvt_i32_f32_e32 v42, v43
	v_cmp_nlt_f32_e32 vcc, s7, v39
	v_ldexp_f32 v41, v41, v42
	s_nop 0
	v_cndmask_b32_e32 v41, 0, v41, vcc
	v_cmp_ngt_f32_e32 vcc, s8, v39
	s_nop 1
	v_cndmask_b32_e32 v42, v192, v41, vcc
	v_mul_f32_e32 v41, 0xbfb8aa3b, v40
	v_fma_f32 v43, v40, s6, -v41
	v_rndne_f32_e32 v44, v41
	v_fmac_f32_e32 v43, 0xb2a5705f, v40
	v_sub_f32_e32 v41, v41, v44
	v_add_f32_e32 v41, v41, v43
	v_exp_f32_e32 v41, v41
	v_cvt_i32_f32_e32 v43, v44
	v_cmp_nlt_f32_e32 vcc, s7, v40
	v_ldexp_f32 v41, v41, v43
	s_nop 0
	v_cndmask_b32_e32 v41, 0, v41, vcc
	v_cmp_ngt_f32_e32 vcc, s8, v40
	s_nop 1
	v_cndmask_b32_e32 v43, v192, v41, vcc
	v_pk_add_f32 v[42:43], v[42:43], 1.0 op_sel_hi:[1,0]
	s_nop 0
	v_div_scale_f32 v41, s[4:5], v43, v43, v40
	v_rcp_f32_e32 v44, v41
	s_nop 0
	v_fma_f32 v45, -v41, v44, 1.0
	v_fmac_f32_e32 v44, v45, v44
	v_div_scale_f32 v45, vcc, v40, v43, v40
	v_mul_f32_e32 v46, v45, v44
	v_fma_f32 v47, -v41, v46, v45
	v_fmac_f32_e32 v46, v47, v44
	v_fma_f32 v41, -v41, v46, v45
	v_div_fmas_f32 v41, v41, v44, v46
	v_div_fixup_f32 v41, v41, v43, v40
	v_div_scale_f32 v40, s[4:5], v42, v42, v39
	v_rcp_f32_e32 v43, v40
	s_nop 0
	v_fma_f32 v44, -v40, v43, 1.0
	v_fmac_f32_e32 v43, v44, v43
	v_div_scale_f32 v44, vcc, v39, v42, v39
	v_mul_f32_e32 v45, v44, v43
	v_fma_f32 v46, -v40, v45, v44
	v_fmac_f32_e32 v45, v46, v43
	v_fma_f32 v40, -v40, v45, v44
	v_div_fmas_f32 v40, v40, v43, v45
	v_div_fixup_f32 v40, v40, v42, v39
	v_pk_mul_f32 v[40:41], v[2:3], v[40:41]
	s_nop 0
	v_cvt_pk_bf16_f32 v39, v40, v41
	global_store_dwordx2 v[66:67], v[38:39], off
	s_waitcnt vmcnt(3)
	v_lshlrev_b32_e32 v38, 16, v36
	v_and_b32_e32 v39, 0xffff0000, v36
	v_mul_f32_e32 v36, 0xbfb8aa3b, v38
	v_lshlrev_b32_e32 v40, 16, v37
	v_and_b32_e32 v41, 0xffff0000, v37
	v_fma_f32 v37, v38, s6, -v36
	v_rndne_f32_e32 v42, v36
	v_fmac_f32_e32 v37, 0xb2a5705f, v38
	v_sub_f32_e32 v36, v36, v42
	v_add_f32_e32 v36, v36, v37
	v_exp_f32_e32 v36, v36
	v_cvt_i32_f32_e32 v37, v42
	v_cmp_nlt_f32_e32 vcc, s7, v38
	v_ldexp_f32 v36, v36, v37
	v_mul_f32_e32 v37, 0xbfb8aa3b, v39
	v_fma_f32 v42, v39, s6, -v37
	v_rndne_f32_e32 v43, v37
	v_fmac_f32_e32 v42, 0xb2a5705f, v39
	v_sub_f32_e32 v37, v37, v43
	v_add_f32_e32 v37, v37, v42
	v_exp_f32_e32 v37, v37
	v_cvt_i32_f32_e32 v42, v43
	v_cndmask_b32_e32 v36, 0, v36, vcc
	v_cmp_ngt_f32_e32 vcc, s8, v38
	v_ldexp_f32 v37, v37, v42
	s_nop 0
	v_cndmask_b32_e32 v36, v192, v36, vcc
	v_cmp_nlt_f32_e32 vcc, s7, v39
	s_nop 1
	v_cndmask_b32_e32 v37, 0, v37, vcc
	v_cmp_ngt_f32_e32 vcc, s8, v39
	s_nop 1
	v_cndmask_b32_e32 v37, v192, v37, vcc
	v_pk_add_f32 v[36:37], v[36:37], 1.0 op_sel_hi:[1,0]
	s_nop 0
	v_div_scale_f32 v42, s[4:5], v37, v37, v39
	v_rcp_f32_e32 v43, v42
	s_nop 0
	v_fma_f32 v44, -v42, v43, 1.0
	v_fmac_f32_e32 v43, v44, v43
	v_div_scale_f32 v44, vcc, v39, v37, v39
	v_mul_f32_e32 v45, v44, v43
	v_fma_f32 v46, -v42, v45, v44
	v_fmac_f32_e32 v45, v46, v43
	v_fma_f32 v42, -v42, v45, v44
	v_div_fmas_f32 v42, v42, v43, v45
	v_div_fixup_f32 v37, v42, v37, v39
	v_div_scale_f32 v39, s[4:5], v36, v36, v38
	v_rcp_f32_e32 v42, v39
	s_nop 0
	v_fma_f32 v43, -v39, v42, 1.0
	v_fmac_f32_e32 v42, v43, v42
	v_div_scale_f32 v43, vcc, v38, v36, v38
	v_mul_f32_e32 v44, v43, v42
	v_fma_f32 v45, -v39, v44, v43
	v_fmac_f32_e32 v44, v45, v42
	v_fma_f32 v39, -v39, v44, v43
	v_div_fmas_f32 v39, v39, v42, v44
	v_div_fixup_f32 v36, v39, v36, v38
	v_pk_mul_f32 v[36:37], v[4:5], v[36:37]
	v_cmp_nlt_f32_e32 vcc, s7, v40
	v_cvt_pk_bf16_f32 v36, v36, v37
	v_mul_f32_e32 v37, 0xbfb8aa3b, v40
	v_fma_f32 v38, v40, s6, -v37
	v_rndne_f32_e32 v39, v37
	v_fmac_f32_e32 v38, 0xb2a5705f, v40
	v_sub_f32_e32 v37, v37, v39
	v_add_f32_e32 v37, v37, v38
	v_exp_f32_e32 v37, v37
	v_cvt_i32_f32_e32 v38, v39
	v_ldexp_f32 v37, v37, v38
	v_cndmask_b32_e32 v37, 0, v37, vcc
	v_cmp_ngt_f32_e32 vcc, s8, v40
	s_nop 1
	v_cndmask_b32_e32 v38, v192, v37, vcc
	v_mul_f32_e32 v37, 0xbfb8aa3b, v41
	v_fma_f32 v39, v41, s6, -v37
	v_rndne_f32_e32 v42, v37
	v_fmac_f32_e32 v39, 0xb2a5705f, v41
	v_sub_f32_e32 v37, v37, v42
	v_add_f32_e32 v37, v37, v39
	v_exp_f32_e32 v37, v37
	v_cvt_i32_f32_e32 v39, v42
	v_cmp_nlt_f32_e32 vcc, s7, v41
	v_ldexp_f32 v37, v37, v39
	s_nop 0
	v_cndmask_b32_e32 v37, 0, v37, vcc
	v_cmp_ngt_f32_e32 vcc, s8, v41
	s_nop 1
	v_cndmask_b32_e32 v39, v192, v37, vcc
	v_pk_add_f32 v[38:39], v[38:39], 1.0 op_sel_hi:[1,0]
	s_nop 0
	v_div_scale_f32 v37, s[4:5], v39, v39, v41
	v_rcp_f32_e32 v42, v37
	s_nop 0
	v_fma_f32 v43, -v37, v42, 1.0
	v_fmac_f32_e32 v42, v43, v42
	v_div_scale_f32 v43, vcc, v41, v39, v41
	v_mul_f32_e32 v44, v43, v42
	v_fma_f32 v45, -v37, v44, v43
	v_fmac_f32_e32 v44, v45, v42
	v_fma_f32 v37, -v37, v44, v43
	v_div_fmas_f32 v37, v37, v42, v44
	v_div_fixup_f32 v39, v37, v39, v41
	v_div_scale_f32 v37, s[4:5], v38, v38, v40
	v_rcp_f32_e32 v41, v37
	s_nop 0
	v_fma_f32 v42, -v37, v41, 1.0
	v_fmac_f32_e32 v41, v42, v41
	v_div_scale_f32 v42, vcc, v40, v38, v40
	v_mul_f32_e32 v43, v42, v41
	v_fma_f32 v44, -v37, v43, v42
	v_fmac_f32_e32 v43, v44, v41
	v_fma_f32 v37, -v37, v43, v42
	v_div_fmas_f32 v37, v37, v41, v43
	v_div_fixup_f32 v38, v37, v38, v40
	v_pk_mul_f32 v[38:39], v[6:7], v[38:39]
	s_nop 0
	v_cvt_pk_bf16_f32 v37, v38, v39
	global_store_dwordx2 v[66:67], v[36:37], off offset:16
	s_waitcnt vmcnt(3)
	v_lshlrev_b32_e32 v36, 16, v34
	v_and_b32_e32 v37, 0xffff0000, v34
	v_mul_f32_e32 v34, 0xbfb8aa3b, v36
	v_lshlrev_b32_e32 v38, 16, v35
	v_and_b32_e32 v39, 0xffff0000, v35
	v_fma_f32 v35, v36, s6, -v34
	v_rndne_f32_e32 v40, v34
	v_fmac_f32_e32 v35, 0xb2a5705f, v36
	v_sub_f32_e32 v34, v34, v40
	v_add_f32_e32 v34, v34, v35
	v_exp_f32_e32 v34, v34
	v_cvt_i32_f32_e32 v35, v40
	v_cmp_nlt_f32_e32 vcc, s7, v36
	v_ldexp_f32 v34, v34, v35
	v_mul_f32_e32 v35, 0xbfb8aa3b, v37
	v_fma_f32 v40, v37, s6, -v35
	v_rndne_f32_e32 v41, v35
	v_fmac_f32_e32 v40, 0xb2a5705f, v37
	v_sub_f32_e32 v35, v35, v41
	v_add_f32_e32 v35, v35, v40
	v_exp_f32_e32 v35, v35
	v_cvt_i32_f32_e32 v40, v41
	v_cndmask_b32_e32 v34, 0, v34, vcc
	v_cmp_ngt_f32_e32 vcc, s8, v36
	v_ldexp_f32 v35, v35, v40
	s_nop 0
	v_cndmask_b32_e32 v34, v192, v34, vcc
	v_cmp_nlt_f32_e32 vcc, s7, v37
	s_nop 1
	v_cndmask_b32_e32 v35, 0, v35, vcc
	v_cmp_ngt_f32_e32 vcc, s8, v37
	s_nop 1
	v_cndmask_b32_e32 v35, v192, v35, vcc
	v_pk_add_f32 v[34:35], v[34:35], 1.0 op_sel_hi:[1,0]
	s_nop 0
	v_div_scale_f32 v40, s[4:5], v35, v35, v37
	v_rcp_f32_e32 v41, v40
	s_nop 0
	v_fma_f32 v42, -v40, v41, 1.0
	v_fmac_f32_e32 v41, v42, v41
	v_div_scale_f32 v42, vcc, v37, v35, v37
	v_mul_f32_e32 v43, v42, v41
	v_fma_f32 v44, -v40, v43, v42
	v_fmac_f32_e32 v43, v44, v41
	v_fma_f32 v40, -v40, v43, v42
	v_div_fmas_f32 v40, v40, v41, v43
	v_div_fixup_f32 v35, v40, v35, v37
	v_div_scale_f32 v37, s[4:5], v34, v34, v36
	v_rcp_f32_e32 v40, v37
	s_nop 0
	v_fma_f32 v41, -v37, v40, 1.0
	v_fmac_f32_e32 v40, v41, v40
	v_div_scale_f32 v41, vcc, v36, v34, v36
	v_mul_f32_e32 v42, v41, v40
	v_fma_f32 v43, -v37, v42, v41
	v_fmac_f32_e32 v42, v43, v40
	v_fma_f32 v37, -v37, v42, v41
	v_div_fmas_f32 v37, v37, v40, v42
	v_div_fixup_f32 v34, v37, v34, v36
	v_pk_mul_f32 v[34:35], v[8:9], v[34:35]
	v_cmp_nlt_f32_e32 vcc, s7, v38
	v_cvt_pk_bf16_f32 v34, v34, v35
	v_mul_f32_e32 v35, 0xbfb8aa3b, v38
	v_fma_f32 v36, v38, s6, -v35
	v_rndne_f32_e32 v37, v35
	v_fmac_f32_e32 v36, 0xb2a5705f, v38
	v_sub_f32_e32 v35, v35, v37
	v_add_f32_e32 v35, v35, v36
	v_exp_f32_e32 v35, v35
	v_cvt_i32_f32_e32 v36, v37
	v_ldexp_f32 v35, v35, v36
	v_cndmask_b32_e32 v35, 0, v35, vcc
	v_cmp_ngt_f32_e32 vcc, s8, v38
	s_nop 1
	v_cndmask_b32_e32 v36, v192, v35, vcc
	v_mul_f32_e32 v35, 0xbfb8aa3b, v39
	v_fma_f32 v37, v39, s6, -v35
	v_rndne_f32_e32 v40, v35
	v_fmac_f32_e32 v37, 0xb2a5705f, v39
	v_sub_f32_e32 v35, v35, v40
	v_add_f32_e32 v35, v35, v37
	v_exp_f32_e32 v35, v35
	v_cvt_i32_f32_e32 v37, v40
	v_cmp_nlt_f32_e32 vcc, s7, v39
	v_ldexp_f32 v35, v35, v37
	s_nop 0
	v_cndmask_b32_e32 v35, 0, v35, vcc
	v_cmp_ngt_f32_e32 vcc, s8, v39
	s_nop 1
	v_cndmask_b32_e32 v37, v192, v35, vcc
	v_pk_add_f32 v[36:37], v[36:37], 1.0 op_sel_hi:[1,0]
	s_nop 0
	v_div_scale_f32 v35, s[4:5], v37, v37, v39
	v_rcp_f32_e32 v40, v35
	s_nop 0
	v_fma_f32 v41, -v35, v40, 1.0
	v_fmac_f32_e32 v40, v41, v40
	v_div_scale_f32 v41, vcc, v39, v37, v39
	v_mul_f32_e32 v42, v41, v40
	v_fma_f32 v43, -v35, v42, v41
	v_fmac_f32_e32 v42, v43, v40
	v_fma_f32 v35, -v35, v42, v41
	v_div_fmas_f32 v35, v35, v40, v42
	v_div_fixup_f32 v37, v35, v37, v39
	v_div_scale_f32 v35, s[4:5], v36, v36, v38
	v_rcp_f32_e32 v39, v35
	s_nop 0
	v_fma_f32 v40, -v35, v39, 1.0
	v_fmac_f32_e32 v39, v40, v39
	v_div_scale_f32 v40, vcc, v38, v36, v38
	v_mul_f32_e32 v41, v40, v39
	v_fma_f32 v42, -v35, v41, v40
	v_fmac_f32_e32 v41, v42, v39
	v_fma_f32 v35, -v35, v41, v40
	v_div_fmas_f32 v35, v35, v39, v41
	v_div_fixup_f32 v36, v35, v36, v38
	v_pk_mul_f32 v[36:37], v[10:11], v[36:37]
	s_nop 0
	v_cvt_pk_bf16_f32 v35, v36, v37
	global_store_dwordx2 v[66:67], v[34:35], off offset:32
	s_waitcnt vmcnt(3)
	v_lshlrev_b32_e32 v34, 16, v32
	v_and_b32_e32 v35, 0xffff0000, v32
	v_mul_f32_e32 v32, 0xbfb8aa3b, v34
	v_lshlrev_b32_e32 v36, 16, v33
	v_and_b32_e32 v37, 0xffff0000, v33
	v_fma_f32 v33, v34, s6, -v32
	v_rndne_f32_e32 v38, v32
	v_fmac_f32_e32 v33, 0xb2a5705f, v34
	v_sub_f32_e32 v32, v32, v38
	v_add_f32_e32 v32, v32, v33
	v_exp_f32_e32 v32, v32
	v_cvt_i32_f32_e32 v33, v38
	v_cmp_nlt_f32_e32 vcc, s7, v34
	v_ldexp_f32 v32, v32, v33
	v_mul_f32_e32 v33, 0xbfb8aa3b, v35
	v_fma_f32 v38, v35, s6, -v33
	v_rndne_f32_e32 v39, v33
	v_fmac_f32_e32 v38, 0xb2a5705f, v35
	v_sub_f32_e32 v33, v33, v39
	v_add_f32_e32 v33, v33, v38
	v_exp_f32_e32 v33, v33
	v_cvt_i32_f32_e32 v38, v39
	v_cndmask_b32_e32 v32, 0, v32, vcc
	v_cmp_ngt_f32_e32 vcc, s8, v34
	v_ldexp_f32 v33, v33, v38
	s_nop 0
	v_cndmask_b32_e32 v32, v192, v32, vcc
	v_cmp_nlt_f32_e32 vcc, s7, v35
	s_nop 1
	v_cndmask_b32_e32 v33, 0, v33, vcc
	v_cmp_ngt_f32_e32 vcc, s8, v35
	s_nop 1
	v_cndmask_b32_e32 v33, v192, v33, vcc
	v_pk_add_f32 v[32:33], v[32:33], 1.0 op_sel_hi:[1,0]
	s_nop 0
	v_div_scale_f32 v38, s[4:5], v33, v33, v35
	v_rcp_f32_e32 v39, v38
	s_nop 0
	v_fma_f32 v40, -v38, v39, 1.0
	v_fmac_f32_e32 v39, v40, v39
	v_div_scale_f32 v40, vcc, v35, v33, v35
	v_mul_f32_e32 v41, v40, v39
	v_fma_f32 v42, -v38, v41, v40
	v_fmac_f32_e32 v41, v42, v39
	v_fma_f32 v38, -v38, v41, v40
	v_div_fmas_f32 v38, v38, v39, v41
	v_div_fixup_f32 v33, v38, v33, v35
	v_div_scale_f32 v35, s[4:5], v32, v32, v34
	v_rcp_f32_e32 v38, v35
	s_nop 0
	v_fma_f32 v39, -v35, v38, 1.0
	v_fmac_f32_e32 v38, v39, v38
	v_div_scale_f32 v39, vcc, v34, v32, v34
	v_mul_f32_e32 v40, v39, v38
	v_fma_f32 v41, -v35, v40, v39
	v_fmac_f32_e32 v40, v41, v38
	v_fma_f32 v35, -v35, v40, v39
	v_div_fmas_f32 v35, v35, v38, v40
	v_div_fixup_f32 v32, v35, v32, v34
	v_pk_mul_f32 v[32:33], v[12:13], v[32:33]
	v_cmp_nlt_f32_e32 vcc, s7, v36
	v_cvt_pk_bf16_f32 v32, v32, v33
	v_mul_f32_e32 v33, 0xbfb8aa3b, v36
	v_fma_f32 v34, v36, s6, -v33
	v_rndne_f32_e32 v35, v33
	v_fmac_f32_e32 v34, 0xb2a5705f, v36
	v_sub_f32_e32 v33, v33, v35
	v_add_f32_e32 v33, v33, v34
	v_exp_f32_e32 v33, v33
	v_cvt_i32_f32_e32 v34, v35
	v_ldexp_f32 v33, v33, v34
	v_cndmask_b32_e32 v33, 0, v33, vcc
	v_cmp_ngt_f32_e32 vcc, s8, v36
	s_nop 1
	v_cndmask_b32_e32 v34, v192, v33, vcc
	v_mul_f32_e32 v33, 0xbfb8aa3b, v37
	v_fma_f32 v35, v37, s6, -v33
	v_rndne_f32_e32 v38, v33
	v_fmac_f32_e32 v35, 0xb2a5705f, v37
	v_sub_f32_e32 v33, v33, v38
	v_add_f32_e32 v33, v33, v35
	v_exp_f32_e32 v33, v33
	v_cvt_i32_f32_e32 v35, v38
	v_cmp_nlt_f32_e32 vcc, s7, v37
	v_ldexp_f32 v33, v33, v35
	s_nop 0
	v_cndmask_b32_e32 v33, 0, v33, vcc
	v_cmp_ngt_f32_e32 vcc, s8, v37
	s_nop 1
	v_cndmask_b32_e32 v35, v192, v33, vcc
	v_pk_add_f32 v[34:35], v[34:35], 1.0 op_sel_hi:[1,0]
	s_nop 0
	v_div_scale_f32 v33, s[4:5], v35, v35, v37
	v_rcp_f32_e32 v38, v33
	s_nop 0
	v_fma_f32 v39, -v33, v38, 1.0
	v_fmac_f32_e32 v38, v39, v38
	v_div_scale_f32 v39, vcc, v37, v35, v37
	v_mul_f32_e32 v40, v39, v38
	v_fma_f32 v41, -v33, v40, v39
	v_fmac_f32_e32 v40, v41, v38
	v_fma_f32 v33, -v33, v40, v39
	v_div_fmas_f32 v33, v33, v38, v40
	v_div_fixup_f32 v35, v33, v35, v37
	v_div_scale_f32 v33, s[4:5], v34, v34, v36
	v_rcp_f32_e32 v37, v33
	s_nop 0
	v_fma_f32 v38, -v33, v37, 1.0
	v_fmac_f32_e32 v37, v38, v37
	v_div_scale_f32 v38, vcc, v36, v34, v36
	v_mul_f32_e32 v39, v38, v37
	v_fma_f32 v40, -v33, v39, v38
	v_fmac_f32_e32 v39, v40, v37
	v_fma_f32 v33, -v33, v39, v38
	v_div_fmas_f32 v33, v33, v37, v39
	v_div_fixup_f32 v34, v33, v34, v36
	v_pk_mul_f32 v[34:35], v[14:15], v[34:35]
	s_nop 0
	v_cvt_pk_bf16_f32 v33, v34, v35
	global_store_dwordx2 v[66:67], v[32:33], off offset:48
	s_cbranch_execnz .LBB0_710

.LBB0_717:
	s_waitcnt vmcnt(0)
	s_mov_b64 s[0:1], exec
	s_mov_b64 exec, -1
	v_mov_b32_e32 v222, 0x980
	v_mov_b32_e32 v223, 0x680
	v_mov_b32_e32 v224, 0x900
	v_mov_b32_e32 v225, 0x700
	v_mov_b32_e32 v226, 0x880
	v_mov_b32_e32 v227, 0x780
	v_mov_b32_e32 v228, 0x800
	v_mov_b32_e32 v229, 0x1800
	s_mov_b64 exec, s[0:1]
	s_waitcnt lgkmcnt(0)
	s_barrier
	s_mov_b64 s[0:1], exec
	v_readlane_b32 s2, v252, 16
	v_readlane_b32 s3, v252, 17
	s_and_b64 s[2:3], s[0:1], s[2:3]
	s_mov_b64 exec, s[2:3]
	s_cbranch_execz .LBB0_769
	s_waitcnt vmcnt(0) expcnt(0) lgkmcnt(0)
	ds_read_b32 v2, v179
	ds_read_b32 v0, v180
	s_waitcnt lgkmcnt(1)
	v_cmp_ne_u32_e32 vcc, 0, v2
	s_cbranch_vccnz .LBB0_733
	s_mov_b32 s4, 1
	s_branch .LBB0_721
